# attention softmax: cross-half row max via v_permlane32_swap (no LDS bpermute), exp/sum block re-interleaved without trans-hazard nops, same add order
# baseline (speedup 1.0000x reference)
; __device__ __forceinline__ void attn_phase(LAS unsigned char* lds, const bf16* Q, const bf16* KV, const bf16* KPE, const float* rope, bf16* mix, int bid, int G, int tid) {
;     ...
;                 float mx = fmaxf(S0[0], S1[0]);
; #pragma unroll
;                 for (int e = 1; e < 16; ++e) mx = fmaxf(mx, fmaxf(S0[e], S1[e]));
;                 mx = fmaxf(mx, __shfl_xor(mx, 32));
;                 const float mnew = (mx > mrun + 6.0f) ? mx : mrun;
;                 const float alpha = __builtin_amdgcn_exp2f(mrun - mnew); mrun = mnew;
;                 float rs = 0.f;
; #pragma unroll
;                 for (int e = 0; e < 16; ++e) { S0[e] = __builtin_amdgcn_exp2f(S0[e] - mnew); S1[e] = __builtin_amdgcn_exp2f(S1[e] - mnew); rs += S0[e] + S1[e]; }
;                 lrun = lrun * alpha + rs;
;                 if (__builtin_amdgcn_ballot_w64(alpha != 1.0f) != 0ull) {
; #pragma unroll
;                     for (int i = 0; i < 4; ++i)
; #pragma unroll
;                         for (int e = 0; e < 16; ++e) O[i][e] *= alpha; }
.LBB0_256:
	s_nop 9
	v_max3_f32 v209, v64, v65, v66
	v_max3_f32 v210, v67, v68, v69
	v_max3_f32 v211, v70, v71, v72
	v_max3_f32 v212, v73, v74, v75
	v_max3_f32 v209, v209, v76, v77
	v_max3_f32 v210, v210, v78, v79
	v_max3_f32 v211, v211, v80, v81
	v_max3_f32 v212, v212, v82, v83
	v_max3_f32 v209, v209, v84, v85
	v_max3_f32 v210, v210, v86, v87
	v_max3_f32 v211, v211, v88, v89
	v_max3_f32 v212, v212, v90, v91
	v_max3_f32 v209, v209, v92, v93
	v_max3_f32 v210, v210, v94, v95
	v_max3_f32 v209, v209, v210, v211
	v_max_f32_e32 v209, v209, v212
	v_mov_b32_e32 v210, v209
	s_nop 1
	v_permlane32_swap_b32_e32 v209, v210
	v_max_f32_e32 v209, v209, v210
	v_add_f32_e32 v210, 0x40c00000, v184
	v_cmp_gt_f32_e32 vcc, v209, v210
	s_nop 1
	v_cndmask_b32_e32 v209, v184, v209, vcc
	v_sub_f32_e32 v184, v184, v209
	v_exp_f32_e32 v184, v184
	s_nop 0
	v_cmp_neq_f32_e32 vcc, 1.0, v184
	s_cbranch_vccz .LBB0_258
	v_pk_mul_f32 v[62:63], v[62:63], v[184:185] op_sel_hi:[1,0]
	v_pk_mul_f32 v[60:61], v[60:61], v[184:185] op_sel_hi:[1,0]
	v_pk_mul_f32 v[58:59], v[58:59], v[184:185] op_sel_hi:[1,0]
	v_pk_mul_f32 v[56:57], v[56:57], v[184:185] op_sel_hi:[1,0]
	v_pk_mul_f32 v[54:55], v[54:55], v[184:185] op_sel_hi:[1,0]
	v_pk_mul_f32 v[52:53], v[52:53], v[184:185] op_sel_hi:[1,0]
	v_pk_mul_f32 v[50:51], v[50:51], v[184:185] op_sel_hi:[1,0]
	v_pk_mul_f32 v[48:49], v[48:49], v[184:185] op_sel_hi:[1,0]
	v_pk_mul_f32 v[46:47], v[46:47], v[184:185] op_sel_hi:[1,0]
	v_pk_mul_f32 v[44:45], v[44:45], v[184:185] op_sel_hi:[1,0]
	v_pk_mul_f32 v[42:43], v[42:43], v[184:185] op_sel_hi:[1,0]
	v_pk_mul_f32 v[40:41], v[40:41], v[184:185] op_sel_hi:[1,0]
	v_pk_mul_f32 v[38:39], v[38:39], v[184:185] op_sel_hi:[1,0]
	v_pk_mul_f32 v[36:37], v[36:37], v[184:185] op_sel_hi:[1,0]
	v_pk_mul_f32 v[34:35], v[34:35], v[184:185] op_sel_hi:[1,0]
	v_pk_mul_f32 v[32:33], v[32:33], v[184:185] op_sel_hi:[1,0]
	v_pk_mul_f32 v[30:31], v[30:31], v[184:185] op_sel_hi:[1,0]
	v_pk_mul_f32 v[28:29], v[28:29], v[184:185] op_sel_hi:[1,0]
	v_pk_mul_f32 v[26:27], v[26:27], v[184:185] op_sel_hi:[1,0]
	v_pk_mul_f32 v[24:25], v[24:25], v[184:185] op_sel_hi:[1,0]
	v_pk_mul_f32 v[22:23], v[22:23], v[184:185] op_sel_hi:[1,0]
	v_pk_mul_f32 v[20:21], v[20:21], v[184:185] op_sel_hi:[1,0]
	v_pk_mul_f32 v[18:19], v[18:19], v[184:185] op_sel_hi:[1,0]
	v_pk_mul_f32 v[16:17], v[16:17], v[184:185] op_sel_hi:[1,0]
	v_pk_mul_f32 v[14:15], v[14:15], v[184:185] op_sel_hi:[1,0]
	v_pk_mul_f32 v[12:13], v[12:13], v[184:185] op_sel_hi:[1,0]
	v_pk_mul_f32 v[10:11], v[10:11], v[184:185] op_sel_hi:[1,0]
	v_pk_mul_f32 v[8:9], v[8:9], v[184:185] op_sel_hi:[1,0]
	v_pk_mul_f32 v[6:7], v[6:7], v[184:185] op_sel_hi:[1,0]
	v_pk_mul_f32 v[4:5], v[4:5], v[184:185] op_sel_hi:[1,0]
	v_pk_mul_f32 v[2:3], v[2:3], v[184:185] op_sel_hi:[1,0]
	v_pk_mul_f32 v[0:1], v[0:1], v[184:185] op_sel_hi:[1,0]
; __device__ __forceinline__ u32x4 pack8(const float (&f)[8]) { u32x4 w; w.x = pk_bf16(f[0], f[1]); w.y = pk_bf16(f[2], f[3]); w.z = pk_bf16(f[4], f[5]); w.w = pk_bf16(f[6], f[7]); return w; }
; #define AT_LDV(buf, hs) do { const LAS unsigned char* vp_ = va + ((((hs) >> 1) >> 1) * 32 + 16 * (((hs) >> 1) & 1)) * AT_VROW + ((hs) & 1) * 128; _Pragma("unroll") for (int d_ = 0; d_ < 2; ++d_) { vf[buf][2 * d_] = vtr(vp_ + d_ * 64); vf[buf][2 * d_ + 1] = vtr(vp_ + 8 * AT_VROW + d_ * 64); } } while (0)
; __device__ __forceinline__ void attn_phase(LAS unsigned char* lds, const bf16* Q, const bf16* KV, const bf16* KPE, const float* rope, bf16* mix, int bid, int G, int tid) {
;     ...
;                 float rs = 0.f;
; #pragma unroll
;                 for (int e = 0; e < 16; ++e) { S0[e] = __builtin_amdgcn_exp2f(S0[e] - mnew); S1[e] = __builtin_amdgcn_exp2f(S1[e] - mnew); rs += S0[e] + S1[e]; }
;                 lrun = lrun * alpha + rs;
;     ...
;                 for (int hs = 0; hs < 8; ++hs) { const int st = hs >> 1;
;                     if (hs < 7) { AT_LDV((hs + 1) & 1, hs + 1); }
;                     __builtin_amdgcn_sched_barrier(0);
;                     float pf[8];
; #pragma unroll
;                     for (int e = 0; e < 8; ++e) pf[e] = (st >> 1) ? S1[8 * (st & 1) + e] : S0[8 * (st & 1) + e];
;                     const bf16x8 pb = __builtin_bit_cast(bf16x8, pack8(pf));
; #pragma unroll
;                     for (int d_ = 0; d_ < 2; ++d_) { const int dvt = (hs & 1) * 2 + d_; const s16x4 lo = vf[hs & 1][2 * d_], hi = vf[hs & 1][2 * d_ + 1];
;                         const bf16x8 A = (bf16x8){lo[0], lo[1], lo[2], lo[3], hi[0], hi[1], hi[2], hi[3]};
;                         __builtin_amdgcn_s_setprio(1); O[dvt] = __builtin_amdgcn_mfma_f32_32x32x16_bf16(A, pb, O[dvt], 0, 0, 0); __builtin_amdgcn_s_setprio(0); }
;                     __builtin_amdgcn_sched_barrier(0); }
.LBB0_258:
	v_sub_f32_e32 v250, v80, v209
	v_exp_f32_e32 v80, v250
	v_sub_f32_e32 v250, v64, v209
	v_exp_f32_e32 v210, v250
	v_sub_f32_e32 v250, v81, v209
	v_exp_f32_e32 v81, v250
	v_sub_f32_e32 v250, v65, v209
	v_exp_f32_e32 v211, v250
	v_add_f32_e32 v242, v80, v210
	v_sub_f32_e32 v250, v82, v209
	v_exp_f32_e32 v82, v250
	v_sub_f32_e32 v250, v66, v209
	v_exp_f32_e32 v212, v250
	v_add_f32_e32 v251, v81, v211
	v_add_f32_e32 v242, v251, v242
	v_sub_f32_e32 v250, v83, v209
	v_exp_f32_e32 v83, v250
	v_sub_f32_e32 v250, v67, v209
	v_exp_f32_e32 v213, v250
	v_add_f32_e32 v251, v82, v212
	v_add_f32_e32 v242, v251, v242
	v_sub_f32_e32 v250, v84, v209
	v_exp_f32_e32 v84, v250
	v_sub_f32_e32 v250, v68, v209
	v_exp_f32_e32 v214, v250
	v_add_f32_e32 v251, v83, v213
	v_add_f32_e32 v242, v251, v242
	v_sub_f32_e32 v250, v85, v209
	v_exp_f32_e32 v85, v250
	v_sub_f32_e32 v250, v69, v209
	v_exp_f32_e32 v215, v250
	v_add_f32_e32 v251, v84, v214
	v_add_f32_e32 v242, v251, v242
	v_sub_f32_e32 v250, v86, v209
	v_exp_f32_e32 v86, v250
	v_sub_f32_e32 v250, v70, v209
	v_exp_f32_e32 v228, v250
	v_add_f32_e32 v251, v85, v215
	v_add_f32_e32 v242, v251, v242
	v_sub_f32_e32 v250, v87, v209
	v_exp_f32_e32 v87, v250
	v_sub_f32_e32 v250, v71, v209
	v_exp_f32_e32 v229, v250
	v_add_f32_e32 v251, v86, v228
	v_add_f32_e32 v242, v251, v242
	v_sub_f32_e32 v250, v88, v209
	v_exp_f32_e32 v88, v250
	v_sub_f32_e32 v250, v72, v209
	v_exp_f32_e32 v230, v250
	v_add_f32_e32 v251, v87, v229
	v_add_f32_e32 v242, v251, v242
	v_sub_f32_e32 v250, v89, v209
	v_exp_f32_e32 v89, v250
	v_sub_f32_e32 v250, v73, v209
	v_exp_f32_e32 v231, v250
	v_add_f32_e32 v251, v88, v230
	v_add_f32_e32 v242, v251, v242
	v_sub_f32_e32 v250, v90, v209
	v_exp_f32_e32 v90, v250
	v_sub_f32_e32 v250, v74, v209
	v_exp_f32_e32 v232, v250
	v_add_f32_e32 v251, v89, v231
	v_add_f32_e32 v242, v251, v242
	v_sub_f32_e32 v250, v91, v209
	v_exp_f32_e32 v91, v250
	v_sub_f32_e32 v250, v75, v209
	v_exp_f32_e32 v233, v250
	v_add_f32_e32 v251, v90, v232
	v_add_f32_e32 v242, v251, v242
	v_sub_f32_e32 v250, v92, v209
	v_exp_f32_e32 v92, v250
	v_sub_f32_e32 v250, v76, v209
	v_exp_f32_e32 v234, v250
	v_add_f32_e32 v251, v91, v233
	v_add_f32_e32 v242, v251, v242
	v_sub_f32_e32 v250, v93, v209
	v_exp_f32_e32 v93, v250
	v_sub_f32_e32 v250, v77, v209
	v_exp_f32_e32 v235, v250
	v_add_f32_e32 v251, v92, v234
	v_add_f32_e32 v242, v251, v242
	v_sub_f32_e32 v250, v94, v209
	v_exp_f32_e32 v94, v250
	v_sub_f32_e32 v250, v78, v209
	v_exp_f32_e32 v236, v250
	v_add_f32_e32 v251, v93, v235
	v_add_f32_e32 v242, v251, v242
	v_sub_f32_e32 v250, v95, v209
	v_exp_f32_e32 v95, v250
	v_sub_f32_e32 v250, v79, v209
	v_exp_f32_e32 v237, v250
	v_add_f32_e32 v251, v94, v236
	v_add_f32_e32 v242, v251, v242
	s_nop 0
	v_add_f32_e32 v251, v95, v237
	v_add_f32_e32 v242, v251, v242
	ds_read_b64_tr_b16 v[64:65], v208 offset:25728
	ds_read_b64_tr_b16 v[66:67], v208 offset:28288
	ds_read_b64_tr_b16 v[68:69], v208 offset:25792
	ds_read_b64_tr_b16 v[70:71], v208 offset:28352
	v_fmac_f32_e32 v242, v207, v184
	v_cvt_pk_bf16_f32 v72, v80, v81
	v_cvt_pk_bf16_f32 v73, v82, v83
	v_cvt_pk_bf16_f32 v74, v84, v85
	v_cvt_pk_bf16_f32 v75, v86, v87
	s_setprio 1
	s_nop 0
	s_waitcnt lgkmcnt(4)
	v_mfma_f32_32x32x16_bf16 v[48:63], v[170:173], v[72:75], v[48:63]
	s_setprio 0
	s_setprio 1
	v_mfma_f32_32x32x16_bf16 v[32:47], v[166:169], v[72:75], v[32:47]
	s_setprio 0
	ds_read_b64_tr_b16 v[76:77], v208 offset:30720
	ds_read_b64_tr_b16 v[78:79], v208 offset:33280
	ds_read_b64_tr_b16 v[80:81], v208 offset:30784
	ds_read_b64_tr_b16 v[82:83], v208 offset:33344
	s_setprio 1
	s_waitcnt lgkmcnt(0)
	v_mfma_f32_32x32x16_bf16 v[16:31], v[64:67], v[72:75], v[16:31]
	s_setprio 0
	s_setprio 1
	v_mfma_f32_32x32x16_bf16 v[0:15], v[68:71], v[72:75], v[0:15]
	s_setprio 0
	ds_read_b64_tr_b16 v[64:65], v208 offset:30848
	ds_read_b64_tr_b16 v[66:67], v208 offset:33408
	ds_read_b64_tr_b16 v[68:69], v208 offset:30912
	ds_read_b64_tr_b16 v[70:71], v208 offset:33472
	v_cvt_pk_bf16_f32 v72, v88, v89
	v_cvt_pk_bf16_f32 v73, v90, v91
	v_cvt_pk_bf16_f32 v74, v92, v93
	v_cvt_pk_bf16_f32 v75, v94, v95
	s_setprio 1
	s_nop 0
	v_mfma_f32_32x32x16_bf16 v[48:63], v[76:79], v[72:75], v[48:63]
	s_setprio 0
	s_setprio 1
	v_mfma_f32_32x32x16_bf16 v[32:47], v[80:83], v[72:75], v[32:47]
	s_setprio 0
	ds_read_b64_tr_b16 v[76:77], v208 offset:35840
	ds_read_b64_tr_b16 v[78:79], v208 offset:38400
	ds_read_b64_tr_b16 v[82:83], v208 offset:38464
	ds_read_b64_tr_b16 v[80:81], v208 offset:35904
	s_setprio 1
	s_waitcnt lgkmcnt(0)
	v_mfma_f32_32x32x16_bf16 v[16:31], v[64:67], v[72:75], v[16:31]
	s_setprio 0
	s_setprio 1
	v_mfma_f32_32x32x16_bf16 v[0:15], v[68:71], v[72:75], v[0:15]
	s_setprio 0
	ds_read_b64_tr_b16 v[64:65], v208 offset:35968
	ds_read_b64_tr_b16 v[66:67], v208 offset:38528
	ds_read_b64_tr_b16 v[70:71], v208 offset:38592
	ds_read_b64_tr_b16 v[68:69], v208 offset:36032
	v_cvt_pk_bf16_f32 v72, v210, v211
	v_cvt_pk_bf16_f32 v73, v212, v213
	v_cvt_pk_bf16_f32 v74, v214, v215
	v_cvt_pk_bf16_f32 v75, v228, v229
	s_setprio 1
	s_nop 0
	v_mfma_f32_32x32x16_bf16 v[48:63], v[76:79], v[72:75], v[48:63]
	s_setprio 0
	s_setprio 1
	v_mfma_f32_32x32x16_bf16 v[32:47], v[80:83], v[72:75], v[32:47]
	s_setprio 0
	ds_read_b64_tr_b16 v[76:77], v208 offset:40960
	ds_read_b64_tr_b16 v[78:79], v208 offset:43520
	ds_read_b64_tr_b16 v[82:83], v208 offset:43584
	ds_read_b64_tr_b16 v[80:81], v208 offset:41024
	s_setprio 1
	s_waitcnt lgkmcnt(0)
	v_mfma_f32_32x32x16_bf16 v[16:31], v[64:67], v[72:75], v[16:31]
	s_setprio 0
	s_setprio 1
	v_mfma_f32_32x32x16_bf16 v[0:15], v[68:71], v[72:75], v[0:15]
	s_setprio 0
	ds_read_b64_tr_b16 v[64:65], v208 offset:41088
	ds_read_b64_tr_b16 v[66:67], v208 offset:43648
	ds_read_b64_tr_b16 v[70:71], v208 offset:43712
	ds_read_b64_tr_b16 v[68:69], v208 offset:41152
	v_cvt_pk_bf16_f32 v72, v230, v231
	v_cvt_pk_bf16_f32 v73, v232, v233
	v_cvt_pk_bf16_f32 v74, v234, v235
	v_cvt_pk_bf16_f32 v75, v236, v237
	s_setprio 1
	s_nop 0
	v_mfma_f32_32x32x16_bf16 v[48:63], v[76:79], v[72:75], v[48:63]
	s_setprio 0
	s_setprio 1
	v_mfma_f32_32x32x16_bf16 v[32:47], v[80:83], v[72:75], v[32:47]
	s_setprio 0
	s_setprio 1
	s_waitcnt lgkmcnt(0)
	v_mfma_f32_32x32x16_bf16 v[16:31], v[64:67], v[72:75], v[16:31]
	s_setprio 0
	s_setprio 1
	v_mfma_f32_32x32x16_bf16 v[0:15], v[68:71], v[72:75], v[0:15]
	s_setprio 0
	v_mov_b32_e32 v207, v242
	s_andn2_b64 vcc, exec, s[34:35]
	s_cbranch_vccz .LBB0_260
	s_branch .LBB0_261
